# phase-1 RoPE epilogue: rope-table rows loaded three row groups ahead into rotating register sets, counted vmcnt instead of vmcnt(0) per group (stores of the previous group no longer drained); on v068
# speedup vs baseline: 1.0133x; 1.0088x over previous
.LBB0_178:
	ds_read_b128 v[148:151], v159
	ds_read_b128 v[152:155], v159 offset:1024
	ds_read_b128 v[164:167], v159 offset:2048
	ds_read_b128 v[168:171], v159 offset:3072
	s_add_u32 s52, s50, 0xfffc0080
	s_addc_u32 s53, s51, -1
	s_cmp_eq_u32 s92, 12
	s_cselect_b32 s55, s11, s53
	s_cselect_b32 s54, s13, s52
	s_cselect_b32 s53, s17, s91
	s_cselect_b32 s52, s43, s45
	v_lshl_add_u64 v[156:157], s[50:51], 0, v[140:141]
	s_add_i32 m0, s58, 0xc000
	ds_read_b128 v[172:175], v160
	ds_read_b128 v[176:179], v160 offset:1024
	ds_read_b128 v[180:183], v160 offset:2048
	ds_read_b128 v[184:187], v160 offset:3072
	ds_read_b128 v[188:191], v160 offset:4096
	ds_read_b128 v[196:199], v160 offset:5120
	ds_read_b128 v[200:203], v160 offset:6144
	ds_read_b128 v[204:207], v160 offset:7168
	global_load_lds_dwordx4 v[156:157], off
	v_lshl_add_u64 v[156:157], s[50:51], 0, v[142:143]
	s_add_i32 m0, s58, 0xe000
	s_nop 0
	global_load_lds_dwordx4 v[156:157], off
	s_waitcnt lgkmcnt(8)
	s_barrier
	s_waitcnt lgkmcnt(0)
	s_setprio 1
	s_waitcnt lgkmcnt(0)
	v_mfma_f32_16x16x32_bf16 v[124:127], v[148:151], v[172:175], v[124:127]
	v_mfma_f32_16x16x32_bf16 v[120:123], v[164:167], v[172:175], v[120:123]
	v_mfma_f32_16x16x32_bf16 v[108:111], v[148:151], v[180:183], v[108:111]
	v_mfma_f32_16x16x32_bf16 v[104:107], v[164:167], v[180:183], v[104:107]
	v_mfma_f32_16x16x32_bf16 v[92:95], v[148:151], v[188:191], v[92:95]
	v_mfma_f32_16x16x32_bf16 v[88:91], v[164:167], v[188:191], v[88:91]
	v_mfma_f32_16x16x32_bf16 v[76:79], v[148:151], v[200:203], v[76:79]
	v_mfma_f32_16x16x32_bf16 v[72:75], v[164:167], v[200:203], v[72:75]
	v_mfma_f32_16x16x32_bf16 v[124:127], v[152:155], v[176:179], v[124:127]
	v_mfma_f32_16x16x32_bf16 v[120:123], v[168:171], v[176:179], v[120:123]
	v_mfma_f32_16x16x32_bf16 v[108:111], v[152:155], v[184:187], v[108:111]
	v_mfma_f32_16x16x32_bf16 v[104:107], v[168:171], v[184:187], v[104:107]
	v_mfma_f32_16x16x32_bf16 v[92:95], v[152:155], v[196:199], v[92:95]
	v_mfma_f32_16x16x32_bf16 v[88:91], v[168:171], v[196:199], v[88:91]
	v_mfma_f32_16x16x32_bf16 v[76:79], v[152:155], v[204:207], v[76:79]
	v_mfma_f32_16x16x32_bf16 v[72:75], v[168:171], v[204:207], v[72:75]
	s_setprio 0
	s_barrier
	s_add_i32 s93, s89, s57
	v_lshl_add_u64 v[156:157], s[52:53], 0, v[130:131]
	s_mov_b32 m0, s93
	ds_read_b128 v[208:211], v161
	ds_read_b128 v[212:215], v161 offset:1024
	ds_read_b128 v[216:219], v161 offset:2048
	ds_read_b128 v[220:223], v161 offset:3072
	global_load_lds_dwordx4 v[156:157], off
	v_lshl_add_u64 v[224:225], s[52:53], 0, v[134:135]
	s_add_i32 m0, s93, 0x2000
	s_nop 0
	global_load_lds_dwordx4 v[224:225], off
	s_barrier
	s_waitcnt lgkmcnt(0)
	s_setprio 1
	s_waitcnt lgkmcnt(0)
	v_mfma_f32_16x16x32_bf16 v[116:119], v[208:211], v[172:175], v[116:119]
	v_mfma_f32_16x16x32_bf16 v[112:115], v[216:219], v[172:175], v[112:115]
	v_mfma_f32_16x16x32_bf16 v[100:103], v[208:211], v[180:183], v[100:103]
	v_mfma_f32_16x16x32_bf16 v[96:99], v[216:219], v[180:183], v[96:99]
	v_mfma_f32_16x16x32_bf16 v[84:87], v[208:211], v[188:191], v[84:87]
	v_mfma_f32_16x16x32_bf16 v[80:83], v[216:219], v[188:191], v[80:83]
	v_mfma_f32_16x16x32_bf16 v[68:71], v[208:211], v[200:203], v[68:71]
	v_mfma_f32_16x16x32_bf16 v[64:67], v[216:219], v[200:203], v[64:67]
	v_mfma_f32_16x16x32_bf16 v[116:119], v[212:215], v[176:179], v[116:119]
	v_mfma_f32_16x16x32_bf16 v[112:115], v[220:223], v[176:179], v[112:115]
	v_mfma_f32_16x16x32_bf16 v[100:103], v[212:215], v[184:187], v[100:103]
	v_mfma_f32_16x16x32_bf16 v[96:99], v[220:223], v[184:187], v[96:99]
	v_mfma_f32_16x16x32_bf16 v[84:87], v[212:215], v[196:199], v[84:87]
	v_mfma_f32_16x16x32_bf16 v[80:83], v[220:223], v[196:199], v[80:83]
	v_mfma_f32_16x16x32_bf16 v[68:71], v[212:215], v[204:207], v[68:71]
	v_mfma_f32_16x16x32_bf16 v[64:67], v[220:223], v[204:207], v[64:67]
	s_setprio 0
	s_mov_b32 m0, s58
	v_lshl_add_u64 v[226:227], s[54:55], 0, v[128:129]
	s_barrier
	ds_read_b128 v[172:175], v160 offset:16384
	ds_read_b128 v[176:179], v160 offset:17408
	ds_read_b128 v[180:183], v160 offset:18432
	ds_read_b128 v[184:187], v160 offset:19456
	ds_read_b128 v[188:191], v160 offset:20480
	ds_read_b128 v[196:199], v160 offset:21504
	ds_read_b128 v[200:203], v160 offset:22528
	ds_read_b128 v[204:207], v160 offset:23552
	global_load_lds_dwordx4 v[226:227], off
	v_lshl_add_u64 v[228:229], s[54:55], 0, v[132:133]
	s_mov_b32 m0, s59
	s_nop 0
	global_load_lds_dwordx4 v[228:229], off
	s_barrier
	s_waitcnt lgkmcnt(0)
	s_setprio 1
	s_waitcnt lgkmcnt(0)
	v_mfma_f32_16x16x32_bf16 v[60:63], v[148:151], v[172:175], v[60:63]
	v_mfma_f32_16x16x32_bf16 v[56:59], v[164:167], v[172:175], v[56:59]
	v_mfma_f32_16x16x32_bf16 v[44:47], v[148:151], v[180:183], v[44:47]
	v_mfma_f32_16x16x32_bf16 v[40:43], v[164:167], v[180:183], v[40:43]
	v_mfma_f32_16x16x32_bf16 v[28:31], v[148:151], v[188:191], v[28:31]
	v_mfma_f32_16x16x32_bf16 v[24:27], v[164:167], v[188:191], v[24:27]
	v_mfma_f32_16x16x32_bf16 v[12:15], v[148:151], v[200:203], v[12:15]
	v_mfma_f32_16x16x32_bf16 v[8:11], v[164:167], v[200:203], v[8:11]
	v_mfma_f32_16x16x32_bf16 v[60:63], v[152:155], v[176:179], v[60:63]
	v_mfma_f32_16x16x32_bf16 v[56:59], v[168:171], v[176:179], v[56:59]
	v_mfma_f32_16x16x32_bf16 v[44:47], v[152:155], v[184:187], v[44:47]
	v_mfma_f32_16x16x32_bf16 v[40:43], v[168:171], v[184:187], v[40:43]
	v_mfma_f32_16x16x32_bf16 v[28:31], v[152:155], v[196:199], v[28:31]
	v_mfma_f32_16x16x32_bf16 v[24:27], v[168:171], v[196:199], v[24:27]
	v_mfma_f32_16x16x32_bf16 v[12:15], v[152:155], v[204:207], v[12:15]
	v_mfma_f32_16x16x32_bf16 v[8:11], v[168:171], v[204:207], v[8:11]
	s_setprio 0
	s_barrier
	s_add_u32 s94, s52, 0x10000
	s_addc_u32 s95, s53, 0
	s_add_i32 s93, s90, s57
	v_lshl_add_u64 v[148:149], s[94:95], 0, v[130:131]
	s_mov_b32 m0, s93
	s_nop 0
	global_load_lds_dwordx4 v[148:149], off
	v_lshl_add_u64 v[148:149], s[94:95], 0, v[134:135]
	s_add_i32 m0, s93, 0x2000
	s_nop 0
	global_load_lds_dwordx4 v[148:149], off
	s_waitcnt vmcnt(6)
	s_barrier
	s_setprio 1
	v_mfma_f32_16x16x32_bf16 v[52:55], v[208:211], v[172:175], v[52:55]
	v_mfma_f32_16x16x32_bf16 v[48:51], v[216:219], v[172:175], v[48:51]
	v_mfma_f32_16x16x32_bf16 v[36:39], v[208:211], v[180:183], v[36:39]
	v_mfma_f32_16x16x32_bf16 v[32:35], v[216:219], v[180:183], v[32:35]
	v_mfma_f32_16x16x32_bf16 v[20:23], v[208:211], v[188:191], v[20:23]
	v_mfma_f32_16x16x32_bf16 v[16:19], v[216:219], v[188:191], v[16:19]
	v_mfma_f32_16x16x32_bf16 v[4:7], v[208:211], v[200:203], v[4:7]
	v_mfma_f32_16x16x32_bf16 v[0:3], v[216:219], v[200:203], v[0:3]
	v_mfma_f32_16x16x32_bf16 v[52:55], v[212:215], v[176:179], v[52:55]
	v_mfma_f32_16x16x32_bf16 v[48:51], v[220:223], v[176:179], v[48:51]
	v_mfma_f32_16x16x32_bf16 v[36:39], v[212:215], v[184:187], v[36:39]
	v_mfma_f32_16x16x32_bf16 v[32:35], v[220:223], v[184:187], v[32:35]
	v_mfma_f32_16x16x32_bf16 v[20:23], v[212:215], v[196:199], v[20:23]
	v_mfma_f32_16x16x32_bf16 v[16:19], v[220:223], v[196:199], v[16:19]
	v_mfma_f32_16x16x32_bf16 v[4:7], v[212:215], v[204:207], v[4:7]
	v_mfma_f32_16x16x32_bf16 v[0:3], v[220:223], v[204:207], v[0:3]
	s_setprio 0
	s_add_i32 s93, 0, 0x18000
	v_add_u32_e32 v136, s93, v158
	s_barrier
	ds_read_b128 v[148:151], v136
	ds_read_b128 v[152:155], v136 offset:1024
	ds_read_b128 v[164:167], v136 offset:2048
	ds_read_b128 v[168:171], v136 offset:3072
	s_add_u32 s54, s54, 0x40000
	s_addc_u32 s55, s55, 0
	s_mov_b32 m0, s60
	v_lshl_add_u64 v[208:209], s[54:55], 0, v[128:129]
	ds_read_b128 v[172:175], v160 offset:32768
	ds_read_b128 v[176:179], v160 offset:33792
	ds_read_b128 v[180:183], v160 offset:34816
	ds_read_b128 v[184:187], v160 offset:35840
	ds_read_b128 v[188:191], v160 offset:36864
	ds_read_b128 v[196:199], v160 offset:37888
	ds_read_b128 v[200:203], v160 offset:38912
	ds_read_b128 v[204:207], v160 offset:39936
	global_load_lds_dwordx4 v[208:209], off
	v_lshl_add_u64 v[208:209], s[54:55], 0, v[132:133]
	s_mov_b32 m0, s61
	s_nop 0
	global_load_lds_dwordx4 v[208:209], off
	s_waitcnt lgkmcnt(8)
	s_barrier
	s_waitcnt lgkmcnt(0)
	s_setprio 1
	s_waitcnt lgkmcnt(0)
	v_mfma_f32_16x16x32_bf16 v[124:127], v[148:151], v[172:175], v[124:127]
	v_mfma_f32_16x16x32_bf16 v[120:123], v[164:167], v[172:175], v[120:123]
	v_mfma_f32_16x16x32_bf16 v[108:111], v[148:151], v[180:183], v[108:111]
	v_mfma_f32_16x16x32_bf16 v[104:107], v[164:167], v[180:183], v[104:107]
	v_mfma_f32_16x16x32_bf16 v[92:95], v[148:151], v[188:191], v[92:95]
	v_mfma_f32_16x16x32_bf16 v[88:91], v[164:167], v[188:191], v[88:91]
	v_mfma_f32_16x16x32_bf16 v[76:79], v[148:151], v[200:203], v[76:79]
	v_mfma_f32_16x16x32_bf16 v[72:75], v[164:167], v[200:203], v[72:75]
	v_mfma_f32_16x16x32_bf16 v[124:127], v[152:155], v[176:179], v[124:127]
	v_mfma_f32_16x16x32_bf16 v[120:123], v[168:171], v[176:179], v[120:123]
	v_mfma_f32_16x16x32_bf16 v[108:111], v[152:155], v[184:187], v[108:111]
	v_mfma_f32_16x16x32_bf16 v[104:107], v[168:171], v[184:187], v[104:107]
	v_mfma_f32_16x16x32_bf16 v[92:95], v[152:155], v[196:199], v[92:95]
	v_mfma_f32_16x16x32_bf16 v[88:91], v[168:171], v[196:199], v[88:91]
	v_mfma_f32_16x16x32_bf16 v[76:79], v[152:155], v[204:207], v[76:79]
	v_mfma_f32_16x16x32_bf16 v[72:75], v[168:171], v[204:207], v[72:75]
	s_setprio 0
	s_barrier
	s_add_i32 s54, 0, 0x1c000
	s_add_i32 s55, s93, s57
	v_add_u32_e32 v136, s54, v158
	v_lshl_add_u64 v[156:157], v[156:157], 0, s[0:1]
	s_mov_b32 m0, s55
	ds_read_b128 v[208:211], v136
	ds_read_b128 v[212:215], v136 offset:1024
	ds_read_b128 v[216:219], v136 offset:2048
	ds_read_b128 v[220:223], v136 offset:3072
	global_load_lds_dwordx4 v[156:157], off
	v_lshl_add_u64 v[156:157], v[224:225], 0, s[0:1]
	s_add_i32 m0, s55, 0x2000
	s_nop 0
	global_load_lds_dwordx4 v[156:157], off
	s_barrier
	s_waitcnt lgkmcnt(0)
	s_setprio 1
	s_waitcnt lgkmcnt(0)
	v_mfma_f32_16x16x32_bf16 v[116:119], v[208:211], v[172:175], v[116:119]
	v_mfma_f32_16x16x32_bf16 v[112:115], v[216:219], v[172:175], v[112:115]
	v_mfma_f32_16x16x32_bf16 v[100:103], v[208:211], v[180:183], v[100:103]
	v_mfma_f32_16x16x32_bf16 v[96:99], v[216:219], v[180:183], v[96:99]
	v_mfma_f32_16x16x32_bf16 v[84:87], v[208:211], v[188:191], v[84:87]
	v_mfma_f32_16x16x32_bf16 v[80:83], v[216:219], v[188:191], v[80:83]
	v_mfma_f32_16x16x32_bf16 v[68:71], v[208:211], v[200:203], v[68:71]
	v_mfma_f32_16x16x32_bf16 v[64:67], v[216:219], v[200:203], v[64:67]
	v_mfma_f32_16x16x32_bf16 v[116:119], v[212:215], v[176:179], v[116:119]
	v_mfma_f32_16x16x32_bf16 v[112:115], v[220:223], v[176:179], v[112:115]
	v_mfma_f32_16x16x32_bf16 v[100:103], v[212:215], v[184:187], v[100:103]
	v_mfma_f32_16x16x32_bf16 v[96:99], v[220:223], v[184:187], v[96:99]
	v_mfma_f32_16x16x32_bf16 v[84:87], v[212:215], v[196:199], v[84:87]
	v_mfma_f32_16x16x32_bf16 v[80:83], v[220:223], v[196:199], v[80:83]
	v_mfma_f32_16x16x32_bf16 v[68:71], v[212:215], v[204:207], v[68:71]
	v_mfma_f32_16x16x32_bf16 v[64:67], v[220:223], v[204:207], v[64:67]
	s_setprio 0
	s_mov_b32 m0, s65
	v_lshl_add_u64 v[156:157], v[226:227], 0, s[0:1]
	s_barrier
	ds_read_b128 v[172:175], v160 offset:49152
	ds_read_b128 v[176:179], v160 offset:50176
	ds_read_b128 v[180:183], v160 offset:51200
	ds_read_b128 v[184:187], v160 offset:52224
	ds_read_b128 v[188:191], v160 offset:53248
	ds_read_b128 v[196:199], v160 offset:54272
	ds_read_b128 v[200:203], v160 offset:55296
	ds_read_b128 v[204:207], v160 offset:56320
	global_load_lds_dwordx4 v[156:157], off
	v_lshl_add_u64 v[156:157], v[228:229], 0, s[0:1]
	s_mov_b32 m0, s66
	s_nop 0
	global_load_lds_dwordx4 v[156:157], off
	s_barrier
	s_waitcnt lgkmcnt(0)
	s_setprio 1
	s_waitcnt lgkmcnt(0)
	v_mfma_f32_16x16x32_bf16 v[60:63], v[148:151], v[172:175], v[60:63]
	v_mfma_f32_16x16x32_bf16 v[56:59], v[164:167], v[172:175], v[56:59]
	v_mfma_f32_16x16x32_bf16 v[44:47], v[148:151], v[180:183], v[44:47]
	v_mfma_f32_16x16x32_bf16 v[40:43], v[164:167], v[180:183], v[40:43]
	v_mfma_f32_16x16x32_bf16 v[28:31], v[148:151], v[188:191], v[28:31]
	v_mfma_f32_16x16x32_bf16 v[24:27], v[164:167], v[188:191], v[24:27]
	v_mfma_f32_16x16x32_bf16 v[12:15], v[148:151], v[200:203], v[12:15]
	v_mfma_f32_16x16x32_bf16 v[8:11], v[164:167], v[200:203], v[8:11]
	v_mfma_f32_16x16x32_bf16 v[60:63], v[152:155], v[176:179], v[60:63]
	v_mfma_f32_16x16x32_bf16 v[56:59], v[168:171], v[176:179], v[56:59]
	v_mfma_f32_16x16x32_bf16 v[44:47], v[152:155], v[184:187], v[44:47]
	v_mfma_f32_16x16x32_bf16 v[40:43], v[168:171], v[184:187], v[40:43]
	v_mfma_f32_16x16x32_bf16 v[28:31], v[152:155], v[196:199], v[28:31]
	v_mfma_f32_16x16x32_bf16 v[24:27], v[168:171], v[196:199], v[24:27]
	v_mfma_f32_16x16x32_bf16 v[12:15], v[152:155], v[204:207], v[12:15]
	v_mfma_f32_16x16x32_bf16 v[8:11], v[168:171], v[204:207], v[8:11]
	s_setprio 0
	s_barrier
	s_add_u32 s52, s52, 0x10080
	s_addc_u32 s53, s53, 0
	s_add_i32 s54, s54, s57
	v_lshl_add_u64 v[148:149], s[52:53], 0, v[130:131]
	s_mov_b32 m0, s54
	s_nop 0
	global_load_lds_dwordx4 v[148:149], off
	v_lshl_add_u64 v[148:149], s[52:53], 0, v[134:135]
	s_add_i32 m0, s54, 0x2000
	s_nop 0
	global_load_lds_dwordx4 v[148:149], off
	s_waitcnt vmcnt(6)
	s_barrier
	s_setprio 1
	v_mfma_f32_16x16x32_bf16 v[52:55], v[208:211], v[172:175], v[52:55]
	v_mfma_f32_16x16x32_bf16 v[48:51], v[216:219], v[172:175], v[48:51]
	v_mfma_f32_16x16x32_bf16 v[36:39], v[208:211], v[180:183], v[36:39]
	v_mfma_f32_16x16x32_bf16 v[32:35], v[216:219], v[180:183], v[32:35]
	v_mfma_f32_16x16x32_bf16 v[20:23], v[208:211], v[188:191], v[20:23]
	v_mfma_f32_16x16x32_bf16 v[16:19], v[216:219], v[188:191], v[16:19]
	v_mfma_f32_16x16x32_bf16 v[4:7], v[208:211], v[200:203], v[4:7]
	v_mfma_f32_16x16x32_bf16 v[0:3], v[216:219], v[200:203], v[0:3]
	v_mfma_f32_16x16x32_bf16 v[52:55], v[212:215], v[176:179], v[52:55]
	v_mfma_f32_16x16x32_bf16 v[48:51], v[220:223], v[176:179], v[48:51]
	v_mfma_f32_16x16x32_bf16 v[36:39], v[212:215], v[184:187], v[36:39]
	v_mfma_f32_16x16x32_bf16 v[32:35], v[220:223], v[184:187], v[32:35]
	v_mfma_f32_16x16x32_bf16 v[20:23], v[212:215], v[196:199], v[20:23]
	v_mfma_f32_16x16x32_bf16 v[16:19], v[220:223], v[196:199], v[16:19]
	v_mfma_f32_16x16x32_bf16 v[4:7], v[212:215], v[204:207], v[4:7]
	v_mfma_f32_16x16x32_bf16 v[0:3], v[220:223], v[204:207], v[0:3]
	s_setprio 0
	s_add_i32 s92, s92, 2
	s_add_u32 s50, s50, 0x100
	s_addc_u32 s51, s51, 0
	s_add_u32 s45, s45, 0x100
	s_addc_u32 s91, s91, 0
	s_cmp_gt_u32 s92, 13
	s_barrier
	s_cbranch_scc0 .LBB0_178
	s_cmp_lt_i32 s10, 4
	s_cselect_b64 s[52:53], -1, 0
	v_lshl_add_u32 v148, s12, 8, v139
	s_and_b64 vcc, exec, s[52:53]
	s_cbranch_vccz .LBB0_183
	v_and_b32_e32 v149, 64, v162
	v_xor_b32_e32 v136, 16, v162
	v_add_u32_e32 v149, 64, v149
	v_cmp_lt_i32_e32 vcc, v136, v149
	s_nop 1
	v_cndmask_b32_e32 v136, v162, v136, vcc
	v_lshlrev_b32_e32 v136, 2, v136
	ds_bpermute_b32 v156, v136, v124
	ds_bpermute_b32 v152, v136, v120
	ds_bpermute_b32 v157, v136, v125
	ds_bpermute_b32 v153, v136, v121
	ds_bpermute_b32 v154, v136, v126
	ds_bpermute_b32 v150, v136, v122
	ds_bpermute_b32 v155, v136, v127
	ds_bpermute_b32 v151, v136, v123
	s_and_saveexec_b64 s[12:13], s[2:3]
	s_cbranch_execz .LBB0_182
	v_lshlrev_b32_e32 v190, 6, v148
	global_load_dwordx4 v[196:199], v190, s[84:85] offset:32
	global_load_dwordx4 v[200:203], v190, s[84:85] offset:48
	global_load_dwordx4 v[204:207], v190, s[84:85]
	global_load_dwordx4 v[208:211], v190, s[84:85] offset:16
	v_add_u32_e32 v191, 0x400, v190
	global_load_dwordx4 v[212:215], v191, s[84:85] offset:32
	global_load_dwordx4 v[216:219], v191, s[84:85] offset:48
	global_load_dwordx4 v[220:223], v191, s[84:85]
	global_load_dwordx4 v[224:227], v191, s[84:85] offset:16
	v_add_u32_e32 v191, 0x800, v190
	global_load_dwordx4 v[228:231], v191, s[84:85] offset:32
	global_load_dwordx4 v[232:235], v191, s[84:85] offset:48
	global_load_dwordx4 v[236:239], v191, s[84:85]
	global_load_dwordx4 v[186:189], v191, s[84:85] offset:16
	s_waitcnt vmcnt(8)
	v_xor_b32_e32 v136, 0x80000000, v196
	v_xor_b32_e32 v149, 0x80000000, v197
	v_xor_b32_e32 v163, 0x80000000, v198
	v_xor_b32_e32 v180, 0x80000000, v199
	v_xor_b32_e32 v181, 0x80000000, v200
	v_xor_b32_e32 v182, 0x80000000, v201
	v_xor_b32_e32 v183, 0x80000000, v202
	v_xor_b32_e32 v184, 0x80000000, v203
	v_cndmask_b32_e64 v199, v199, v180, s[4:5]
	v_cndmask_b32_e64 v198, v198, v163, s[4:5]
	v_cndmask_b32_e64 v197, v197, v149, s[4:5]
	v_cndmask_b32_e64 v196, v196, v136, s[4:5]
	v_cndmask_b32_e64 v203, v203, v184, s[4:5]
	v_cndmask_b32_e64 v202, v202, v183, s[4:5]
	v_cndmask_b32_e64 v201, v201, v182, s[4:5]
	v_cndmask_b32_e64 v200, v200, v181, s[4:5]
	s_waitcnt lgkmcnt(0)
	v_pk_mul_f32 v[156:157], v[196:197], v[156:157]
	v_pk_mul_f32 v[154:155], v[198:199], v[154:155]
	v_pk_mul_f32 v[152:153], v[200:201], v[152:153]
	v_pk_mul_f32 v[150:151], v[202:203], v[150:151]
	v_pk_fma_f32 v[126:127], v[126:127], v[206:207], v[154:155]
	v_pk_fma_f32 v[124:125], v[124:125], v[204:205], v[156:157]
	v_pk_fma_f32 v[122:123], v[122:123], v[210:211], v[150:151]
	v_pk_fma_f32 v[120:121], v[120:121], v[208:209], v[152:153]
	v_add_u32_e32 v191, 0xc00, v190
	global_load_dwordx4 v[196:199], v191, s[84:85] offset:32
	global_load_dwordx4 v[200:203], v191, s[84:85] offset:48
	global_load_dwordx4 v[204:207], v191, s[84:85]
	global_load_dwordx4 v[208:211], v191, s[84:85] offset:16

.LBB0_191:
	v_cndmask_b32_e64 v113, v118, v123, s[6:7]
	v_cndmask_b32_e64 v114, v120, v122, s[6:7]
	v_cndmask_b32_e64 v123, v121, v126, s[6:7]
	v_cndmask_b32_e64 v121, v118, v113, s[6:7]
	v_cndmask_b32_e64 v113, 0, 1, s[52:53]
	v_cndmask_b32_e64 v122, v119, v125, s[6:7]
	v_cndmask_b32_e64 v120, v120, v114, s[6:7]
	v_cmp_ne_u32_e64 s[12:13], 1, v113
	s_andn2_b64 vcc, exec, s[52:53]
	v_or_b32_e32 v114, 16, v148
	global_store_dwordx4 v[116:117], v[120:123], off
	s_cbranch_vccnz .LBB0_195
	v_and_b32_e32 v115, 64, v162
	v_xor_b32_e32 v113, 16, v162
	v_add_u32_e32 v115, 64, v115
	v_cmp_lt_i32_e32 vcc, v113, v115
	s_nop 1
	v_cndmask_b32_e32 v113, v162, v113, vcc
	v_lshlrev_b32_e32 v113, 2, v113
	ds_bpermute_b32 v122, v113, v108
	ds_bpermute_b32 v118, v113, v104
	ds_bpermute_b32 v123, v113, v109
	ds_bpermute_b32 v119, v113, v105
	ds_bpermute_b32 v120, v113, v110
	ds_bpermute_b32 v116, v113, v106
	ds_bpermute_b32 v121, v113, v111
	ds_bpermute_b32 v117, v113, v107
	s_and_saveexec_b64 s[10:11], s[2:3]
	s_cbranch_execz .LBB0_194
	s_waitcnt vmcnt(10)
	v_xor_b32_e32 v113, 0x80000000, v212
	v_xor_b32_e32 v115, 0x80000000, v213
	v_xor_b32_e32 v125, 0x80000000, v214
	v_xor_b32_e32 v126, 0x80000000, v215
	v_xor_b32_e32 v136, 0x80000000, v216
	v_xor_b32_e32 v149, 0x80000000, v217
	v_xor_b32_e32 v151, 0x80000000, v218
	v_xor_b32_e32 v156, 0x80000000, v219
	v_cndmask_b32_e64 v127, v215, v126, s[4:5]
	v_cndmask_b32_e64 v126, v214, v125, s[4:5]
	v_cndmask_b32_e64 v213, v213, v115, s[4:5]
	v_cndmask_b32_e64 v212, v212, v113, s[4:5]
	v_cndmask_b32_e64 v215, v219, v156, s[4:5]
	v_cndmask_b32_e64 v214, v218, v151, s[4:5]
	v_cndmask_b32_e64 v157, v217, v149, s[4:5]
	v_cndmask_b32_e64 v156, v216, v136, s[4:5]
	s_waitcnt lgkmcnt(5)
	v_pk_mul_f32 v[122:123], v[212:213], v[122:123]
	s_waitcnt lgkmcnt(1)
	v_pk_mul_f32 v[120:121], v[126:127], v[120:121]
	v_pk_mul_f32 v[118:119], v[156:157], v[118:119]
	s_waitcnt lgkmcnt(0)
	v_pk_mul_f32 v[116:117], v[214:215], v[116:117]
	v_pk_fma_f32 v[110:111], v[110:111], v[222:223], v[120:121]
	v_pk_fma_f32 v[108:109], v[108:109], v[220:221], v[122:123]
	v_pk_fma_f32 v[106:107], v[106:107], v[226:227], v[116:117]
	v_pk_fma_f32 v[104:105], v[104:105], v[224:225], v[118:119]
	v_add_u32_e32 v191, 0x2000, v190
	global_load_dwordx4 v[212:215], v191, s[84:85] offset:32
	global_load_dwordx4 v[216:219], v191, s[84:85] offset:48
	global_load_dwordx4 v[220:223], v191, s[84:85]
	global_load_dwordx4 v[224:227], v191, s[84:85] offset:16

.LBB0_203:
	v_cndmask_b32_e64 v96, v101, v105, s[6:7]
	v_cndmask_b32_e64 v97, v100, v104, s[6:7]
	v_cndmask_b32_e64 v103, v103, v108, s[6:7]
	v_cndmask_b32_e64 v102, v102, v107, s[6:7]
	v_cndmask_b32_e64 v101, v101, v96, s[6:7]
	v_cndmask_b32_e64 v100, v100, v97, s[6:7]
	s_and_b64 vcc, exec, s[12:13]
	v_or_b32_e32 v96, 32, v148
	global_store_dwordx4 v[98:99], v[100:103], off
	s_cbranch_vccnz .LBB0_207
	v_and_b32_e32 v98, 64, v162
	v_xor_b32_e32 v97, 16, v162
	v_add_u32_e32 v98, 64, v98
	v_cmp_lt_i32_e32 vcc, v97, v98
	s_nop 1
	v_cndmask_b32_e32 v97, v162, v97, vcc
	v_lshlrev_b32_e32 v97, 2, v97
	ds_bpermute_b32 v104, v97, v92
	ds_bpermute_b32 v100, v97, v88
	ds_bpermute_b32 v105, v97, v93
	ds_bpermute_b32 v101, v97, v89
	ds_bpermute_b32 v102, v97, v94
	ds_bpermute_b32 v98, v97, v90
	ds_bpermute_b32 v103, v97, v95
	ds_bpermute_b32 v99, v97, v91
	s_and_saveexec_b64 s[52:53], s[2:3]
	s_cbranch_execz .LBB0_206
	s_waitcnt vmcnt(12)
	v_xor_b32_e32 v97, 0x80000000, v228
	v_xor_b32_e32 v107, 0x80000000, v229
	v_xor_b32_e32 v113, 0x80000000, v230
	v_xor_b32_e32 v126, 0x80000000, v231
	v_xor_b32_e32 v127, 0x80000000, v232
	v_xor_b32_e32 v136, 0x80000000, v233
	v_xor_b32_e32 v149, 0x80000000, v234
	v_xor_b32_e32 v151, 0x80000000, v235
	v_cndmask_b32_e64 v231, v231, v126, s[4:5]
	v_cndmask_b32_e64 v230, v230, v113, s[4:5]
	v_cndmask_b32_e64 v229, v229, v107, s[4:5]
	v_cndmask_b32_e64 v228, v228, v97, s[4:5]
	v_cndmask_b32_e64 v235, v235, v151, s[4:5]
	v_cndmask_b32_e64 v234, v234, v149, s[4:5]
	v_cndmask_b32_e64 v233, v233, v136, s[4:5]
	v_cndmask_b32_e64 v232, v232, v127, s[4:5]
	s_waitcnt lgkmcnt(5)
	v_pk_mul_f32 v[104:105], v[228:229], v[104:105]
	s_waitcnt lgkmcnt(1)
	v_pk_mul_f32 v[102:103], v[230:231], v[102:103]
	v_pk_mul_f32 v[100:101], v[232:233], v[100:101]
	s_waitcnt lgkmcnt(0)
	v_pk_mul_f32 v[98:99], v[234:235], v[98:99]
	v_pk_fma_f32 v[94:95], v[94:95], v[238:239], v[102:103]
	v_pk_fma_f32 v[92:93], v[92:93], v[236:237], v[104:105]
	v_pk_fma_f32 v[90:91], v[90:91], v[188:189], v[98:99]
	v_pk_fma_f32 v[88:89], v[88:89], v[186:187], v[100:101]
	v_add_u32_e32 v191, 0x2400, v190
	global_load_dwordx4 v[228:231], v191, s[84:85] offset:32
	global_load_dwordx4 v[232:235], v191, s[84:85] offset:48
	global_load_dwordx4 v[236:239], v191, s[84:85]
	global_load_dwordx4 v[186:189], v191, s[84:85] offset:16

.LBB0_215:
	v_cndmask_b32_e64 v80, v85, v89, s[6:7]
	v_cndmask_b32_e64 v81, v84, v88, s[6:7]
	v_cndmask_b32_e64 v87, v87, v92, s[6:7]
	v_cndmask_b32_e64 v86, v86, v91, s[6:7]
	v_cndmask_b32_e64 v85, v85, v80, s[6:7]
	v_cndmask_b32_e64 v84, v84, v81, s[6:7]
	s_and_b64 vcc, exec, s[12:13]
	v_or_b32_e32 v80, 48, v148
	global_store_dwordx4 v[82:83], v[84:87], off
	s_cbranch_vccnz .LBB0_219
	v_and_b32_e32 v82, 64, v162
	v_xor_b32_e32 v81, 16, v162
	v_add_u32_e32 v82, 64, v82
	v_cmp_lt_i32_e32 vcc, v81, v82
	s_nop 1
	v_cndmask_b32_e32 v81, v162, v81, vcc
	v_lshlrev_b32_e32 v81, 2, v81
	ds_bpermute_b32 v88, v81, v76
	ds_bpermute_b32 v84, v81, v72
	ds_bpermute_b32 v89, v81, v77
	ds_bpermute_b32 v85, v81, v73
	ds_bpermute_b32 v86, v81, v78
	ds_bpermute_b32 v82, v81, v74
	ds_bpermute_b32 v87, v81, v79
	ds_bpermute_b32 v83, v81, v75
	s_and_saveexec_b64 s[52:53], s[2:3]
	s_cbranch_execz .LBB0_218
	s_waitcnt vmcnt(14)
	v_xor_b32_e32 v81, 0x80000000, v196
	v_xor_b32_e32 v91, 0x80000000, v197
	v_xor_b32_e32 v108, 0x80000000, v198
	v_xor_b32_e32 v109, 0x80000000, v199
	v_xor_b32_e32 v110, 0x80000000, v200
	v_xor_b32_e32 v111, 0x80000000, v201
	v_xor_b32_e32 v113, 0x80000000, v202
	v_xor_b32_e32 v114, 0x80000000, v203
	v_cndmask_b32_e64 v199, v199, v109, s[4:5]
	v_cndmask_b32_e64 v198, v198, v108, s[4:5]
	v_cndmask_b32_e64 v197, v197, v91, s[4:5]
	v_cndmask_b32_e64 v196, v196, v81, s[4:5]
	v_cndmask_b32_e64 v203, v203, v114, s[4:5]
	v_cndmask_b32_e64 v202, v202, v113, s[4:5]
	v_cndmask_b32_e64 v201, v201, v111, s[4:5]
	v_cndmask_b32_e64 v200, v200, v110, s[4:5]
	s_waitcnt lgkmcnt(5)
	v_pk_mul_f32 v[88:89], v[196:197], v[88:89]
	s_waitcnt lgkmcnt(1)
	v_pk_mul_f32 v[86:87], v[198:199], v[86:87]
	v_pk_mul_f32 v[84:85], v[200:201], v[84:85]
	s_waitcnt lgkmcnt(0)
	v_pk_mul_f32 v[82:83], v[202:203], v[82:83]
	v_pk_fma_f32 v[78:79], v[78:79], v[206:207], v[86:87]
	v_pk_fma_f32 v[76:77], v[76:77], v[204:205], v[88:89]
	v_pk_fma_f32 v[74:75], v[74:75], v[210:211], v[82:83]
	v_pk_fma_f32 v[72:73], v[72:73], v[208:209], v[84:85]
	v_add_u32_e32 v191, 0x2800, v190
	global_load_dwordx4 v[196:199], v191, s[84:85] offset:32
	global_load_dwordx4 v[200:203], v191, s[84:85] offset:48
	global_load_dwordx4 v[204:207], v191, s[84:85]
	global_load_dwordx4 v[208:211], v191, s[84:85] offset:16

.LBB0_227:
	v_cndmask_b32_e64 v64, v69, v73, s[6:7]
	v_cndmask_b32_e64 v65, v68, v72, s[6:7]
	v_cndmask_b32_e64 v71, v71, v75, s[6:7]
	v_cndmask_b32_e64 v70, v70, v74, s[6:7]
	v_cndmask_b32_e64 v69, v69, v64, s[6:7]
	v_cndmask_b32_e64 v68, v68, v65, s[6:7]
	s_and_b64 vcc, exec, s[12:13]
	v_add_u32_e32 v64, 0x80, v148
	global_store_dwordx4 v[66:67], v[68:71], off
	s_cbranch_vccnz .LBB0_231
	v_and_b32_e32 v66, 64, v162
	v_xor_b32_e32 v65, 16, v162
	v_add_u32_e32 v66, 64, v66
	v_cmp_lt_i32_e32 vcc, v65, v66
	s_nop 1
	v_cndmask_b32_e32 v65, v162, v65, vcc
	v_lshlrev_b32_e32 v65, 2, v65
	ds_bpermute_b32 v72, v65, v60
	ds_bpermute_b32 v68, v65, v56
	ds_bpermute_b32 v73, v65, v61
	ds_bpermute_b32 v69, v65, v57
	ds_bpermute_b32 v70, v65, v62
	ds_bpermute_b32 v66, v65, v58
	ds_bpermute_b32 v71, v65, v63
	ds_bpermute_b32 v67, v65, v59
	s_and_saveexec_b64 s[52:53], s[2:3]
	s_cbranch_execz .LBB0_230
	s_waitcnt vmcnt(14)
	v_xor_b32_e32 v65, 0x80000000, v212
	v_xor_b32_e32 v90, 0x80000000, v213
	v_xor_b32_e32 v91, 0x80000000, v214
	v_xor_b32_e32 v92, 0x80000000, v215
	v_xor_b32_e32 v93, 0x80000000, v216
	v_xor_b32_e32 v94, 0x80000000, v217
	v_xor_b32_e32 v95, 0x80000000, v218
	v_xor_b32_e32 v96, 0x80000000, v219
	v_cndmask_b32_e64 v215, v215, v92, s[4:5]
	v_cndmask_b32_e64 v214, v214, v91, s[4:5]
	v_cndmask_b32_e64 v213, v213, v90, s[4:5]
	v_cndmask_b32_e64 v212, v212, v65, s[4:5]
	v_cndmask_b32_e64 v219, v219, v96, s[4:5]
	v_cndmask_b32_e64 v218, v218, v95, s[4:5]
	v_cndmask_b32_e64 v217, v217, v94, s[4:5]
	v_cndmask_b32_e64 v216, v216, v93, s[4:5]
	v_pk_mul_f32 v[72:73], v[212:213], v[72:73]
	v_pk_mul_f32 v[70:71], v[214:215], v[70:71]
	v_pk_mul_f32 v[68:69], v[216:217], v[68:69]
	v_pk_mul_f32 v[66:67], v[218:219], v[66:67]
	v_pk_fma_f32 v[62:63], v[62:63], v[222:223], v[70:71]
	v_pk_fma_f32 v[60:61], v[60:61], v[220:221], v[72:73]
	v_pk_fma_f32 v[58:59], v[58:59], v[226:227], v[66:67]
	v_pk_fma_f32 v[56:57], v[56:57], v[224:225], v[68:69]
	v_add_u32_e32 v191, 0x2c00, v190
	global_load_dwordx4 v[212:215], v191, s[84:85] offset:32
	global_load_dwordx4 v[216:219], v191, s[84:85] offset:48
	global_load_dwordx4 v[220:223], v191, s[84:85]
	global_load_dwordx4 v[224:227], v191, s[84:85] offset:16

.LBB0_239:
	v_cndmask_b32_e64 v48, v53, v57, s[6:7]
	v_cndmask_b32_e64 v49, v52, v56, s[6:7]
	v_cndmask_b32_e64 v55, v55, v60, s[6:7]
	v_cndmask_b32_e64 v54, v54, v59, s[6:7]
	v_cndmask_b32_e64 v53, v53, v48, s[6:7]
	v_cndmask_b32_e64 v52, v52, v49, s[6:7]
	s_and_b64 vcc, exec, s[12:13]
	v_add_u32_e32 v48, 0x90, v148
	global_store_dwordx4 v[50:51], v[52:55], off
	s_cbranch_vccnz .LBB0_243
	v_and_b32_e32 v50, 64, v162
	v_xor_b32_e32 v49, 16, v162
	v_add_u32_e32 v50, 64, v50
	v_cmp_lt_i32_e32 vcc, v49, v50
	s_nop 1
	v_cndmask_b32_e32 v49, v162, v49, vcc
	v_lshlrev_b32_e32 v49, 2, v49
	ds_bpermute_b32 v56, v49, v44
	ds_bpermute_b32 v52, v49, v40
	ds_bpermute_b32 v57, v49, v45
	ds_bpermute_b32 v53, v49, v41
	ds_bpermute_b32 v54, v49, v46
	ds_bpermute_b32 v50, v49, v42
	ds_bpermute_b32 v55, v49, v47
	ds_bpermute_b32 v51, v49, v43
	s_and_saveexec_b64 s[52:53], s[2:3]
	s_cbranch_execz .LBB0_242
	s_waitcnt vmcnt(14)
	v_xor_b32_e32 v49, 0x80000000, v228
	v_xor_b32_e32 v59, 0x80000000, v229
	v_xor_b32_e32 v76, 0x80000000, v230
	v_xor_b32_e32 v77, 0x80000000, v231
	v_xor_b32_e32 v78, 0x80000000, v232
	v_xor_b32_e32 v79, 0x80000000, v233
	v_xor_b32_e32 v80, 0x80000000, v234
	v_xor_b32_e32 v81, 0x80000000, v235
	v_cndmask_b32_e64 v231, v231, v77, s[4:5]
	v_cndmask_b32_e64 v230, v230, v76, s[4:5]
	v_cndmask_b32_e64 v229, v229, v59, s[4:5]
	v_cndmask_b32_e64 v228, v228, v49, s[4:5]
	v_cndmask_b32_e64 v235, v235, v81, s[4:5]
	v_cndmask_b32_e64 v234, v234, v80, s[4:5]
	v_cndmask_b32_e64 v233, v233, v79, s[4:5]
	v_cndmask_b32_e64 v232, v232, v78, s[4:5]
	s_waitcnt lgkmcnt(5)
	v_pk_mul_f32 v[56:57], v[228:229], v[56:57]
	s_waitcnt lgkmcnt(1)
	v_pk_mul_f32 v[54:55], v[230:231], v[54:55]
	v_pk_mul_f32 v[52:53], v[232:233], v[52:53]
	s_waitcnt lgkmcnt(0)
	v_pk_mul_f32 v[50:51], v[234:235], v[50:51]
	v_pk_fma_f32 v[46:47], v[46:47], v[238:239], v[54:55]
	v_pk_fma_f32 v[44:45], v[44:45], v[236:237], v[56:57]
	v_pk_fma_f32 v[42:43], v[42:43], v[188:189], v[50:51]
	v_pk_fma_f32 v[40:41], v[40:41], v[186:187], v[52:53]

.LBB0_251:
	v_cndmask_b32_e64 v32, v37, v41, s[6:7]
	v_cndmask_b32_e64 v33, v36, v40, s[6:7]
	v_cndmask_b32_e64 v39, v39, v44, s[6:7]
	v_cndmask_b32_e64 v38, v38, v43, s[6:7]
	v_cndmask_b32_e64 v37, v37, v32, s[6:7]
	v_cndmask_b32_e64 v36, v36, v33, s[6:7]
	s_and_b64 vcc, exec, s[12:13]
	v_add_u32_e32 v32, 0xa0, v148
	global_store_dwordx4 v[34:35], v[36:39], off
	s_cbranch_vccnz .LBB0_255
	v_and_b32_e32 v34, 64, v162
	v_xor_b32_e32 v33, 16, v162
	v_add_u32_e32 v34, 64, v34
	v_cmp_lt_i32_e32 vcc, v33, v34
	s_nop 1
	v_cndmask_b32_e32 v33, v162, v33, vcc
	v_lshlrev_b32_e32 v33, 2, v33
	ds_bpermute_b32 v40, v33, v28
	ds_bpermute_b32 v36, v33, v24
	ds_bpermute_b32 v41, v33, v29
	ds_bpermute_b32 v37, v33, v25
	ds_bpermute_b32 v38, v33, v30
	ds_bpermute_b32 v34, v33, v26
	ds_bpermute_b32 v39, v33, v31
	ds_bpermute_b32 v35, v33, v27
	s_and_saveexec_b64 s[52:53], s[2:3]
	s_cbranch_execz .LBB0_254
	s_waitcnt vmcnt(10)
	v_xor_b32_e32 v33, 0x80000000, v196
	v_xor_b32_e32 v43, 0x80000000, v197
	v_xor_b32_e32 v60, 0x80000000, v198
	v_xor_b32_e32 v61, 0x80000000, v199
	v_xor_b32_e32 v62, 0x80000000, v200
	v_xor_b32_e32 v63, 0x80000000, v201
	v_xor_b32_e32 v64, 0x80000000, v202
	v_xor_b32_e32 v65, 0x80000000, v203
	v_cndmask_b32_e64 v199, v199, v61, s[4:5]
	v_cndmask_b32_e64 v198, v198, v60, s[4:5]
	v_cndmask_b32_e64 v197, v197, v43, s[4:5]
	v_cndmask_b32_e64 v196, v196, v33, s[4:5]
	v_cndmask_b32_e64 v203, v203, v65, s[4:5]
	v_cndmask_b32_e64 v202, v202, v64, s[4:5]
	v_cndmask_b32_e64 v201, v201, v63, s[4:5]
	v_cndmask_b32_e64 v200, v200, v62, s[4:5]
	s_waitcnt lgkmcnt(5)
	v_pk_mul_f32 v[40:41], v[196:197], v[40:41]
	s_waitcnt lgkmcnt(1)
	v_pk_mul_f32 v[38:39], v[198:199], v[38:39]
	v_pk_mul_f32 v[36:37], v[200:201], v[36:37]
	s_waitcnt lgkmcnt(0)
	v_pk_mul_f32 v[34:35], v[202:203], v[34:35]
	v_pk_fma_f32 v[30:31], v[30:31], v[206:207], v[38:39]
	v_pk_fma_f32 v[28:29], v[28:29], v[204:205], v[40:41]
	v_pk_fma_f32 v[26:27], v[26:27], v[210:211], v[34:35]
	v_pk_fma_f32 v[24:25], v[24:25], v[208:209], v[36:37]

.LBB0_263:
	v_cndmask_b32_e64 v16, v21, v25, s[6:7]
	v_cndmask_b32_e64 v17, v20, v24, s[6:7]
	v_cndmask_b32_e64 v23, v23, v28, s[6:7]
	v_cndmask_b32_e64 v22, v22, v27, s[6:7]
	v_cndmask_b32_e64 v21, v21, v16, s[6:7]
	v_cndmask_b32_e64 v20, v20, v17, s[6:7]
	s_and_b64 vcc, exec, s[12:13]
	v_add_u32_e32 v16, 0xb0, v148
	global_store_dwordx4 v[18:19], v[20:23], off
	s_cbranch_vccnz .LBB0_267
	v_and_b32_e32 v18, 64, v162
	v_xor_b32_e32 v17, 16, v162
	v_add_u32_e32 v18, 64, v18
	v_cmp_lt_i32_e32 vcc, v17, v18
	s_nop 1
	v_cndmask_b32_e32 v17, v162, v17, vcc
	v_lshlrev_b32_e32 v17, 2, v17
	ds_bpermute_b32 v24, v17, v12
	ds_bpermute_b32 v20, v17, v8
	ds_bpermute_b32 v25, v17, v13
	ds_bpermute_b32 v21, v17, v9
	ds_bpermute_b32 v22, v17, v14
	ds_bpermute_b32 v18, v17, v10
	ds_bpermute_b32 v23, v17, v15
	ds_bpermute_b32 v19, v17, v11
	s_and_saveexec_b64 s[12:13], s[2:3]
	s_cbranch_execz .LBB0_266
	s_waitcnt vmcnt(6)
	v_xor_b32_e32 v17, 0x80000000, v212
	v_xor_b32_e32 v27, 0x80000000, v213
	v_xor_b32_e32 v44, 0x80000000, v214
	v_xor_b32_e32 v45, 0x80000000, v215
	v_xor_b32_e32 v46, 0x80000000, v216
	v_xor_b32_e32 v47, 0x80000000, v217
	v_xor_b32_e32 v48, 0x80000000, v218
	v_xor_b32_e32 v49, 0x80000000, v219
	v_cndmask_b32_e64 v215, v215, v45, s[4:5]
	v_cndmask_b32_e64 v214, v214, v44, s[4:5]
	v_cndmask_b32_e64 v213, v213, v27, s[4:5]
	v_cndmask_b32_e64 v212, v212, v17, s[4:5]
	v_cndmask_b32_e64 v219, v219, v49, s[4:5]
	v_cndmask_b32_e64 v218, v218, v48, s[4:5]
	v_cndmask_b32_e64 v217, v217, v47, s[4:5]
	v_cndmask_b32_e64 v216, v216, v46, s[4:5]
	s_waitcnt lgkmcnt(5)
	v_pk_mul_f32 v[24:25], v[212:213], v[24:25]
	s_waitcnt lgkmcnt(1)
	v_pk_mul_f32 v[22:23], v[214:215], v[22:23]
	v_pk_mul_f32 v[20:21], v[216:217], v[20:21]
	s_waitcnt lgkmcnt(0)
	v_pk_mul_f32 v[18:19], v[218:219], v[18:19]
	v_pk_fma_f32 v[14:15], v[14:15], v[222:223], v[22:23]
	v_pk_fma_f32 v[12:13], v[12:13], v[220:221], v[24:25]
	v_pk_fma_f32 v[10:11], v[10:11], v[226:227], v[18:19]
	v_pk_fma_f32 v[8:9], v[8:9], v[224:225], v[20:21]
